# plus pooling pass of rows<16384 run by non-tail workgroups beside the first down-GEMM tail units (arrival counter hand-off)
# speedup vs baseline: 1.0051x; 1.0051x over previous
; #define PG8_BAR __builtin_amdgcn_s_barrier()
; #define PG8_ROW0(u) (tile_row0((u).pm, S.ffn) + (((u).q && (((u).q - 1) & 1)) ? HALF : 0))
; template <class Epi, bool ALIGN_EPI, bool SP2, class Ord = StaticOrder>
; __device__ __forceinline__ void gemm_phase(LAS unsigned char* lds, const Gemm g, const Ord& S, const Epi& E) {
;     ...
;         if constexpr (ALIGN_EPI) { if (wr == 0) PG8_BAR; }
;         E(acc, cur, PG8_ROW0(cur), wr, wc, fr, fq);
;         if (!has_next) break;
; #pragma unroll
;         for (int a = 0; a < 2; ++a)
; #pragma unroll
;             for (int b = 0; b < 2; ++b)
; #pragma unroll
;                 for (int m = 0; m < 4; ++m)
; #pragma unroll
;                     for (int n = 0; n < 2; ++n) acc[a][b][m][n] = (f32x4){0.f, 0.f, 0.f, 0.f};
;         cur = nxt; cA = nA; cB = nB; ntc = PG8_NT(cur); ++ui;
;         if constexpr (ALIGN_EPI) { if (wr == 1) PG8_BAR; }
.LBB0_1487:
	v_readlane_b32 s98, v239, 0
	s_nop 3
	s_cmp_lg_u32 s98, 0
	s_cselect_b32 s101, 0x100, 0
	s_add_i32 s101, s101, 0xc000
	s_waitcnt vmcnt(0)
	s_barrier
	v_cmp_eq_u32_e32 vcc, 0, v0
	s_nop 3
	s_mov_b64 exec, vcc
	s_cbranch_execz .Lfn_a1_x
	v_readlane_b32 s98, v245, 33
	v_readlane_b32 s99, v245, 34
	v_mov_b32_e32 v247, 0
	v_mov_b32_e32 v248, 1
	s_nop 3
	s_add_u32 s98, s98, s101
	s_addc_u32 s99, s99, 0
	global_atomic_add v247, v248, s[98:99]
.Lfn_a1_x:
	s_mov_b64 exec, -1
	s_cmp_eq_u32 s61, 0
	s_cselect_b32 s54, s27, s18
	s_andn2_b64 vcc, exec, s[22:23]
	s_cbranch_vccnz .LBB0_1437
	s_barrier
	s_branch .LBB0_1437

; #define PG8_BAR __builtin_amdgcn_s_barrier()
; #define PG8_ROW0(u) (tile_row0((u).pm, S.ffn) + (((u).q && (((u).q - 1) & 1)) ? HALF : 0))
; template <class Epi, bool ALIGN_EPI, bool SP2, class Ord = StaticOrder>
; __device__ __forceinline__ void gemm_phase(LAS unsigned char* lds, const Gemm g, const Ord& S, const Epi& E) {
;     ...
;         if constexpr (ALIGN_EPI) { if (wr == 0) PG8_BAR; }
;         E(acc, cur, PG8_ROW0(cur), wr, wc, fr, fq);
;         if (!has_next) break;
; #pragma unroll
;         for (int a = 0; a < 2; ++a)
; #pragma unroll
;             for (int b = 0; b < 2; ++b)
; #pragma unroll
;                 for (int m = 0; m < 4; ++m)
; #pragma unroll
;                     for (int n = 0; n < 2; ++n) acc[a][b][m][n] = (f32x4){0.f, 0.f, 0.f, 0.f};
;         cur = nxt; cA = nA; cB = nB; ntc = PG8_NT(cur); ++ui;
;         if constexpr (ALIGN_EPI) { if (wr == 1) PG8_BAR; }
.LBB0_1507:
	s_cmp_lt_u32 s94, 80
	s_cbranch_scc1 .Lfn_skip
	v_readlane_b32 s98, v239, 0
	s_nop 3
	s_cmp_lg_u32 s98, 0
	s_cselect_b32 s101, 0x100, 0
	s_add_i32 s101, s101, 0xc000
	s_waitcnt vmcnt(0)
	s_barrier
	v_cmp_eq_u32_e32 vcc, 0, v0
	s_nop 3
	s_mov_b64 exec, vcc
	s_cbranch_execz .Lfn_a2_x
	v_readlane_b32 s98, v245, 33
	v_readlane_b32 s99, v245, 34
	v_mov_b32_e32 v247, 0
	v_mov_b32_e32 v248, 1
	s_nop 3
	s_add_u32 s98, s98, s101
	s_addc_u32 s99, s99, 0
	global_atomic_add v247, v248, s[98:99]
	s_movk_i32 s100, 0x4000

; #define PHASE_IDS() const int tid = fresh_tid(), lane = tid & 63, wave = __builtin_amdgcn_readfirstlane(tid >> 6), gw = bx * NWAVES + wave; (void)lane; (void)gw
; __global__ void __launch_bounds__(NTHREADS, 2) fwd_megakernel(Params p) {
;     ...
;                 for (int wi = gw; wi < (NPROMPT / 32) * 4; wi += NGW) {
;                     const int cg = wi & 3, rr = (wi >> 2) * 2 + (lane >> 5), c = cg * 256 + (lane & 31) * 8;
;                     const int sq = rr / (LP / 16), t0 = (rr - sq * (LP / 16)) * 16, r0 = sq * LP + t0;
;                     if (cg == 0) pool_run<2, 16>(xb, rss1, nmw, pb, r0, t0, c); else if (cg == 1) pool_run<4, 16>(xb, rss1, nmw, pb, r0, t0, c);
;     ...
;     { PHASE_IDS();
;     auto ld_row = [&](int r, u32x4 (&w)[2]) { if (r < T) { const u32x4* xr = (const u32x4*)(xb + (size_t)r * D) + lane; w[0] = xr[0]; w[1] = xr[64]; } };
;     u32x4 nw[2] = {(u32x4){0u, 0u, 0u, 0u}, (u32x4){0u, 0u, 0u, 0u}}; ld_row(gw, nw);
;     for (int r = gw; r < T; r += NGW) {
;         u32x4 cw2[2] = {nw[0], nw[1]};
;         ld_row(r + NGW, nw);
.Lfn_a2_x:
	s_mov_b64 exec, -1
	s_barrier
	v_readlane_b32 s98, v239, 0
	s_nop 3
	s_cmp_lg_u32 s98, 0
	s_cbranch_scc0 .Lfn_l1
	s_movk_i32 s99, 0x7e57
	s_mov_b32 s98, 0
	s_movk_i32 s100, 0x7ff
	s_movk_i32 s101, 0x580
	s_movk_i32 s24, 0x810
	v_mov_b32_e32 v212, v0
	s_sub_i32 s1, s94, 80
	s_lshl_b32 s1, s1, 3
	s_branch .Lpe_entry
.Lpe_return:
	s_mov_b32 s99, 0
	s_branch .Lfn_skip
.Lfn_l1:
	v_writelane_b32 v247, s3, 0
	v_writelane_b32 v247, s10, 1
	v_writelane_b32 v247, s11, 2
	v_writelane_b32 v247, s12, 3
	v_writelane_b32 v247, s13, 4
	v_writelane_b32 v247, s15, 5
	s_movk_i32 s100, 1408
	s_sub_i32 s1, s94, 80
	s_lshl_b32 s1, s1, 3
	v_readfirstlane_b32 s0, v0
	s_ashr_i32 s0, s0, 6
	s_add_i32 s2, s0, s1
	s_cmpk_gt_i32 s2, 0x3fff
	s_cbranch_scc1 .Lfn_exit
	s_ashr_i32 s3, s2, 31
	s_lshl_b64 s[0:1], s[2:3], 11
	v_and_b32_e32 v63, 63, v0
	s_add_u32 s0, s44, s0
	s_addc_u32 s1, s45, s1
	v_lshlrev_b32_e32 v60, 4, v63
	global_load_dwordx4 v[68:71], v60, s[0:1] offset:1024
	global_load_dwordx4 v[72:75], v60, s[0:1]
	s_add_u32 s13, s88, 0x4000000
	s_addc_u32 s14, s89, 0
	s_add_i32 s0, s2, 0xffffbf80
	s_add_i32 s2, s2, s100
	s_ashr_i32 s3, s2, 31
	s_lshl_b64 s[2:3], s[2:3], 11
	s_add_u32 s2, s90, s2
	v_mov_b32_e32 v61, 0
	s_addc_u32 s3, s91, s3
	s_mov_b64 s[4:5], 0x4a00000
	v_and_b32_e32 v66, 64, v226
	v_lshlrev_b32_e32 v62, 3, v63
	v_lshlrev_b32_e32 v64, 5, v63
	v_mov_b32_e32 v65, v61
	v_lshl_add_u64 v[60:61], s[2:3], 0, v[60:61]
	v_add_u32_e32 v87, 64, v66
	v_lshl_add_u64 v[76:77], s[86:87], 0, v[64:65]
	v_lshlrev_b32_e32 v88, 2, v62
	s_ashr_i32 s101, s100, 31
	v_lshl_add_u64 v[78:79], v[60:61], 0, s[4:5]
	s_mov_b32 s1, 0
	v_mov_b32_e32 v80, 0x358637bd
	s_mov_b32 s12, 0x800000
	v_xor_b32_e32 v81, 1, v226
	v_xor_b32_e32 v82, 2, v226
	v_xor_b32_e32 v83, 4, v226
	v_xor_b32_e32 v84, 8, v226
	v_xor_b32_e32 v85, 16, v226
	v_xor_b32_e32 v86, 32, v226
	s_lshl_b64 s[2:3], s[100:101], 11
	s_waitcnt vmcnt(1)
	v_mov_b64_e32 v[60:61], v[68:69]
	s_waitcnt vmcnt(0)
	v_mov_b64_e32 v[64:65], v[72:73]
	v_mov_b64_e32 v[62:63], v[70:71]
	v_mov_b64_e32 v[66:67], v[74:75]
	s_branch .Lfn_b07

; #define PHASE_IDS() const int tid = fresh_tid(), lane = tid & 63, wave = __builtin_amdgcn_readfirstlane(tid >> 6), gw = bx * NWAVES + wave; (void)lane; (void)gw
; __global__ void __launch_bounds__(NTHREADS, 2) fwd_megakernel(Params p) {
;     ...
;                 PHASE_IDS();
;                 const int gt = bx * NTHREADS + tid, NGT = G * NTHREADS;
;                 const float* rss1 = rss + TP; const float* nmw = norm_mix + D;
;                 for (int wi = gw; wi < (NPROMPT / 32) * 4; wi += NGW) {
;                     const int cg = wi & 3, rr = (wi >> 2) * 2 + (lane >> 5), c = cg * 256 + (lane & 31) * 8;
;                     const int sq = rr / (LP / 16), t0 = (rr - sq * (LP / 16)) * 16, r0 = sq * LP + t0;
;                     if (cg == 0) pool_run<2, 16>(xb, rss1, nmw, pb, r0, t0, c); else if (cg == 1) pool_run<4, 16>(xb, rss1, nmw, pb, r0, t0, c);
.LBB0_1559:
	s_or_b64 exec, exec, s[0:1]
	v_readlane_b32 s0, v239, 0
	v_readlane_b32 s1, v239, 1
	s_andn2_b64 vcc, exec, s[0:1]
	s_mov_b64 s[0:1], -1
	s_waitcnt lgkmcnt(0)
	s_barrier
	s_cbranch_vccnz .LBB0_1085
	s_mov_b32 s99, 0
	s_movk_i32 s98, 0x800
	s_movk_i32 s100, 0x80f
	s_mov_b32 s101, s92
	v_mov_b32_e32 v212, v0
	v_readlane_b32 s1, v245, 49
.Lpe_entry:
	v_readfirstlane_b32 s7, v212
	s_ashr_i32 s0, s7, 6
	s_add_i32 s6, s0, s1
	s_add_i32 s9, s6, s98
	s_cmp_gt_i32 s9, s100
	v_and_b32_e32 v213, 63, v212
	s_cbranch_scc1 .LBB0_1656
	v_lshlrev_b32_e32 v2, 3, v212
	v_and_b32_e32 v2, 0xf8, v2
	s_bfe_u32 s8, s7, 0x20006
	v_lshl_or_b32 v2, s8, 8, v2
	v_readlane_b32 s0, v244, 24
	v_lshlrev_b32_e32 v18, 1, v2
	v_lshlrev_b32_e32 v2, 2, v2
	v_mov_b32_e32 v3, v19
	v_readlane_b32 s1, v244, 25
	v_lshrrev_b32_e32 v214, 5, v213
	v_lshl_add_u64 v[108:109], s[44:45], 0, v[18:19]
	v_lshl_add_u64 v[110:111], s[0:1], 0, v[2:3]
	v_lshl_add_u64 v[112:113], s[70:71], 0, v[18:19]
	s_branch .LBB0_1564

; __global__ void __launch_bounds__(NTHREADS, 2) fwd_megakernel(Params p) {
;     ...
;                 for (int wi = gw; wi < (NPROMPT / 32) * 4; wi += NGW) {
;                     const int cg = wi & 3, rr = (wi >> 2) * 2 + (lane >> 5), c = cg * 256 + (lane & 31) * 8;
;                     const int sq = rr / (LP / 16), t0 = (rr - sq * (LP / 16)) * 16, r0 = sq * LP + t0;
;                     if (cg == 0) pool_run<2, 16>(xb, rss1, nmw, pb, r0, t0, c); else if (cg == 1) pool_run<4, 16>(xb, rss1, nmw, pb, r0, t0, c);
;                     else if (cg == 2) pool_run<8, 16>(xb, rss1, nmw, pb, r0, t0, c);
;                     else { pool_run<16, 8>(xb, rss1, nmw, pb, r0, t0, c); pool_run<16, 8>(xb, rss1, nmw, pb, r0 + 8, t0 + 8, c); }
;                 }
.LBB0_1563:
	s_add_i32 s9, s9, s101
	s_cmp_gt_i32 s9, s100
	s_cbranch_scc1 .LBB0_1656

; __global__ void __launch_bounds__(NTHREADS, 2) fwd_megakernel(Params p) {
;     ...
;                 for (int wi = gw; wi < (NSAMP / 2) * 4; wi += NGW) {
;                     const int cg = wi & 3, r = NPROMPT + (wi >> 2) * 2 + (lane >> 5), c = cg * 256 + (lane & 31) * 8;
;                     if (cg == 0) pool_sample<2>(xb, rss1, nmw, st_pool, pb, r, c); else if (cg == 1) pool_sample<4>(xb, rss1, nmw, st_pool, pb, r, c);
;                     else if (cg == 2) pool_sample<8>(xb, rss1, nmw, st_pool, pb, r, c); else pool_sample<16>(xb, rss1, nmw, st_pool, pb, r, c);
.LBB0_1656:
	s_cmpk_eq_u32 s99, 0x7e57
	s_cbranch_scc1 .Lpe_return
	s_cmpk_gt_i32 s6, 0x7ff
	s_cbranch_scc1 .LBB0_1742
	v_lshrrev_b32_e32 v2, 5, v213
	v_or_b32_e32 v82, 0x4080, v2
	v_lshlrev_b32_e32 v2, 3, v212
	v_and_b32_e32 v2, 0xf8, v2
	s_bfe_u32 s2, s7, 0x20006
	v_lshl_or_b32 v2, s2, 8, v2
	v_readlane_b32 s0, v244, 24
	v_readlane_b32 s8, v245, 3
	v_lshlrev_b32_e32 v18, 2, v2
	v_readlane_b32 s1, v244, 25
	v_readlane_b32 s16, v245, 11
	v_readlane_b32 s17, v245, 12
	v_lshl_add_u64 v[56:57], s[0:1], 0, v[18:19]
	v_lshlrev_b32_e32 v64, 2, v2
	v_lshl_add_u64 v[58:59], s[16:17], 0, v[18:19]
	v_lshlrev_b32_e32 v18, 1, v2
	v_lshl_add_u64 v[60:61], s[44:45], 0, v[18:19]
	v_lshl_add_u64 v[62:63], s[70:71], 0, v[18:19]
	v_readlane_b32 s9, v245, 4
	v_readlane_b32 s10, v245, 5
	v_readlane_b32 s11, v245, 6
	v_readlane_b32 s12, v245, 7
	v_readlane_b32 s13, v245, 8
	v_readlane_b32 s14, v245, 9
	v_readlane_b32 s15, v245, 10
	v_readlane_b32 s18, v245, 13
	v_readlane_b32 s19, v245, 14
	v_readlane_b32 s20, v245, 15
	v_readlane_b32 s21, v245, 16
	v_readlane_b32 s22, v245, 17
	v_readlane_b32 s23, v245, 18
	s_branch .LBB0_1660
